# neighbourhood-attention items: one static priority raise for the second wave group (waves 4-7)
# speedup vs baseline: 1.0013x; 1.0006x over previous
; template <int K> __device__ __forceinline__ float swz(float v) { return __int_as_float(__builtin_amdgcn_ds_swizzle(__float_as_int(v), (K << 10) | 0x1f)); }
; __device__ __forceinline__ float x32_sum(float v) { auto r = __builtin_amdgcn_permlane32_swap(__float_as_uint(v), __float_as_uint(v), false, false); return __uint_as_float(r[0]) + __uint_as_float(r[1]); }
; __device__ __forceinline__ unsigned cvt_pk_bf16(float lo, float hi) { const f32x2c f = {lo, hi}; return __builtin_bit_cast(unsigned, __builtin_convertvector(f, bf16x2c)); }
; __device__ __forceinline__ void na_item(unsigned char* smem, const bf16_t* U, const float* rpb_l, bf16_t* O, int b, int rp, int hp, float shift) {
;     ...
;     { float l = lA; l += swz<16>(l); l = x32_sum(l); const float inv = 1.0f / l;
;       bf16_t* orow = O + qrowA * OW + h * 64 + fq * 4;
; #pragma unroll
;       for (int dg = 0; dg < 4; ++dg) { u32x2_t w; w.x = pg8::cvt_pk_bf16(oA[dg][0] * inv, oA[dg][1] * inv); w.y = pg8::cvt_pk_bf16(oA[dg][2] * inv, oA[dg][3] * inv); *(u32x2_t*)(orow + dg * 16) = w; } }
;     { float l = lB; l += swz<16>(l); l = x32_sum(l); const float inv = 1.0f / l;
;       bf16_t* orow = O + qrowB * OW + h * 64 + fq * 4;
; #pragma unroll
;       for (int dg = 0; dg < 4; ++dg) { u32x2_t w; w.x = pg8::cvt_pk_bf16(oB[dg][0] * inv, oB[dg][1] * inv); w.y = pg8::cvt_pk_bf16(oB[dg][2] * inv, oB[dg][3] * inv); *(u32x2_t*)(orow + dg * 16) = w; } }
.LBB0_820:
	s_setprio 0
	ds_swizzle_b32 v14, v113 offset:swizzle(SWAP,16)
	v_mov_b32_e32 v75, v0
	s_waitcnt lgkmcnt(0)
	v_add_f32_e32 v14, v113, v14
	v_mov_b32_e32 v15, v14
	s_nop 1
	v_permlane32_swap_b32_e32 v14, v15
	v_add_f32_e32 v14, v14, v15
	v_div_scale_f32 v15, s[2:3], v14, v14, 1.0
	v_rcp_f32_e32 v16, v15
	s_nop 0
	v_fma_f32 v17, -v15, v16, 1.0
	v_fmac_f32_e32 v16, v17, v16
	v_div_scale_f32 v17, vcc, 1.0, v14, 1.0
	v_mul_f32_e32 v18, v17, v16
	v_fma_f32 v19, -v15, v18, v17
	v_fmac_f32_e32 v18, v19, v16
	v_fma_f32 v15, -v15, v18, v17
	v_div_fmas_f32 v15, v15, v16, v18
	v_mov_b64_e32 v[16:17], s[66:67]
	v_div_fixup_f32 v14, v15, v14, 1.0
	v_mad_u64_u32 v[16:17], s[2:3], v1, s93, v[16:17]
	v_lshl_add_u64 v[16:17], v[106:107], 1, v[16:17]
	v_pk_mul_f32 v[18:19], v[70:71], v[14:15] op_sel_hi:[1,0]
	v_pk_mul_f32 v[20:21], v[72:73], v[14:15] op_sel_hi:[1,0]
	v_lshl_add_u64 v[16:17], v[74:75], 1, v[16:17]
	v_cvt_pk_bf16_f32 v18, v18, v19
	v_cvt_pk_bf16_f32 v19, v20, v21
	ds_swizzle_b32 v1, v112 offset:swizzle(SWAP,16)
	global_store_dwordx2 v[16:17], v[18:19], off
	v_pk_mul_f32 v[18:19], v[66:67], v[14:15] op_sel_hi:[1,0]
	v_pk_mul_f32 v[20:21], v[68:69], v[14:15] op_sel_hi:[1,0]
	v_cvt_pk_bf16_f32 v18, v18, v19
	v_cvt_pk_bf16_f32 v19, v20, v21
	global_store_dwordx2 v[16:17], v[18:19], off offset:32
	v_pk_mul_f32 v[18:19], v[62:63], v[14:15] op_sel_hi:[1,0]
	v_pk_mul_f32 v[20:21], v[64:65], v[14:15] op_sel_hi:[1,0]
	v_cvt_pk_bf16_f32 v18, v18, v19
	v_cvt_pk_bf16_f32 v19, v20, v21
	global_store_dwordx2 v[16:17], v[18:19], off offset:64
	v_pk_mul_f32 v[18:19], v[58:59], v[14:15] op_sel_hi:[1,0]
	v_pk_mul_f32 v[14:15], v[60:61], v[14:15] op_sel_hi:[1,0]
	s_waitcnt lgkmcnt(0)
	v_add_f32_e32 v1, v112, v1
	v_cvt_pk_bf16_f32 v18, v18, v19
	v_cvt_pk_bf16_f32 v19, v14, v15
	v_mov_b32_e32 v14, v1
	s_nop 1
	v_permlane32_swap_b32_e32 v1, v14
	v_add_f32_e32 v1, v1, v14
	v_div_scale_f32 v14, s[2:3], v1, v1, 1.0
	v_rcp_f32_e32 v15, v14
	global_store_dwordx2 v[16:17], v[18:19], off offset:96
	s_mov_b64 s[2:3], 0x28000
	v_fma_f32 v18, -v14, v15, 1.0
	v_fmac_f32_e32 v15, v18, v15
	v_div_scale_f32 v18, vcc, 1.0, v1, 1.0
	v_mul_f32_e32 v19, v18, v15
	v_fma_f32 v20, -v14, v19, v18
	v_fmac_f32_e32 v19, v20, v15
	v_fma_f32 v14, -v14, v19, v18
	v_div_fmas_f32 v14, v14, v15, v19
	v_div_fixup_f32 v18, v14, v1, 1.0
	v_lshl_add_u64 v[20:21], v[16:17], 0, s[2:3]
	v_pk_mul_f32 v[14:15], v[54:55], v[18:19] op_sel_hi:[1,0]
	v_pk_mul_f32 v[22:23], v[56:57], v[18:19] op_sel_hi:[1,0]
	v_add_co_u32_e32 v16, vcc, 0x28000, v16
	v_cvt_pk_bf16_f32 v148, v14, v15
	v_cvt_pk_bf16_f32 v149, v22, v23
	v_addc_co_u32_e32 v17, vcc, 0, v17, vcc

; __device__ __forceinline__ int otid() { int t = threadIdx.x; asm volatile("" : "+v"(t)); return t; }
; #define LASP __attribute__((address_space(3)))
; __device__ __forceinline__ void na_item(unsigned char* smem, const bf16_t* U, const float* rpb_l, bf16_t* O, int b, int rp, int hp, float shift) {
;     ...
;     const int tid = otid(), lane = tid & 63, wave = tid >> 6, fr = lane & 15, fq = lane >> 4;
;     const int hh = wave >> 2, qg = wave & 3, h = 2 * hp + hh;
;     LASP unsigned char* ls = (LASP unsigned char*)smem;
;     LASP float* bias = (LASP float*)(ls + O_BIAS);
;     const int rA = 2 * rp, rB = rA + 1;
;     const int rsA = min(max(rA - 4, 0), 24), rsB = min(max(rB - 4, 0), 24), dB = rsB - rsA, nst = dB + 8;
;     const int kcol0 = min(max(16 * qg - 8, 0), 32);
;     const int qc = 16 * qg + fr, cs = min(max(qc - 8, 0), 48);
;     const size_t qrowA = (size_t)b * SEQ + rA * 64 + qc, qrowB = qrowA + 64;
;     bf16x8_t qfA[2], qfB[2];
; #pragma unroll
;     for (int kk = 0; kk < 2; ++kk) { qfA[kk] = *(const bf16x8_t*)(U + qrowA * NINP + OQ + h * 64 + kk * 32 + fq * 8); qfB[kk] = *(const bf16x8_t*)(U + qrowB * NINP + OQ + h * 64 + kk * 32 + fq * 8); }
;     f32x4_t oA[4], oB[4];
; #pragma unroll
;     for (int dg = 0; dg < 4; ++dg) { oA[dg] = (f32x4_t){0.f, 0.f, 0.f, 0.f}; oB[dg] = (f32x4_t){0.f, 0.f, 0.f, 0.f}; }
;     float lA = 0.f, lB = 0.f;
;     const float nsh = -shift;
;     const int srow = tid >> 3, sch = tid & 7;
;     const int crow = (tid & 255) >> 3, cisv = tid >> 8;
;     const size_t latbase = ((size_t)b * SEQ + (size_t)rsA * 64 + srow) * NINP + sch * 8;
;     const size_t ctxbase = ((size_t)NLAT + b * CTXL + crow) * NINP + (cisv ? OV : OKK) + sch * 8;
;     u32x4_t rg[6];
;     ...
;     NA_LOAD(0);
;     __syncthreads();
;     for (int i2 = tid; i2 < 2 * 15 * 32; i2 += 512) { const int e = i2 / 480, rr = (i2 % 480) >> 5, x = i2 & 31;
;         bias[i2] = x < 31 ? rpb_l[((2 * hp + e) * 15 + rr) * 31 + x] * LOG2E : 0.f; }
.LBB0_838:
	s_andn2_b64 vcc, exec, s[2:3]
	s_cbranch_vccnz .LBB0_821
	v_readfirstlane_b32 s99, v253
	s_cmp_lt_u32 s99, 0x100
	s_cbranch_scc1 .Lprio_na_skip
	s_setprio 1
.Lprio_na_skip:
	s_lshr_b32 s2, s26, 4
	s_add_i32 s2, s2, s12
	s_and_b32 s3, s13, 15
	s_mul_hi_u32 s5, s2, 0xaaaaaaab
	s_lshr_b32 s16, s5, 1
	s_lshl_b32 s26, s3, 1
	s_mul_i32 s5, s16, 3
	v_mov_b32_e32 v62, v253
	v_sub_u32_e64 v1, s26, 4 clamp
	s_sub_i32 s5, s2, s5
	v_readfirstlane_b32 s2, v1
	v_lshrrev_b32_e32 v1, 2, v62
	v_and_b32_e32 v61, 15, v62
	s_min_u32 s27, s2, 24
	s_waitcnt vmcnt(6)
	v_and_b32_e32 v51, 48, v1
	s_lshl_b32 s17, s16, 11
	s_lshl_b32 s2, s3, 7
	v_ashrrev_i32_e32 v63, 8, v62
	s_lshl_b32 s13, s5, 1
	v_or_b32_e32 v60, v51, v61
	s_or_b32 s2, s17, s2
	v_or_b32_e32 v1, s2, v60
	v_mov_b64_e32 v[2:3], s[68:69]
	v_add_lshl_u32 v106, v63, s13, 6
	v_bfe_u32 v64, v62, 4, 2
	v_mad_u64_u32 v[4:5], s[2:3], v1, s90, v[2:3]
	v_ashrrev_i32_e32 v107, 31, v106
	v_lshl_add_u64 v[4:5], v[106:107], 1, v[4:5]
	v_lshlrev_b32_e32 v108, 4, v64
	v_mov_b32_e32 v109, v0
	v_lshl_add_u64 v[4:5], v[4:5], 0, v[108:109]
	s_mov_b32 s2, 0x48000
	v_add_co_u32_e32 v8, vcc, s2, v4
	v_bfe_u32 v52, v62, 3, 5
	s_lshl_b32 s2, s27, 6
	v_lshl_add_u64 v[6:7], v[4:5], 0, s[34:35]
	v_addc_co_u32_e32 v9, vcc, 0, v5, vcc
	global_load_dwordx4 v[14:17], v[4:5], off
	global_load_dwordx4 v[18:21], v[4:5], off offset:64
	global_load_dwordx4 v[22:25], v[8:9], off
	global_load_dwordx4 v[26:29], v[6:7], off offset:64
	v_ashrrev_i32_e32 v46, 3, v62
	s_or_b32 s54, s2, s17
	v_lshl_or_b32 v5, s16, 8, v52
	s_movk_i32 s2, 0x900
	v_ashrrev_i32_e32 v47, 31, v46
	s_waitcnt vmcnt(9)
	v_mul_lo_u32 v54, v5, s2
	s_movk_i32 s2, 0x100
	v_lshl_add_u64 v[48:49], v[46:47], 0, s[54:55]
	v_cmp_gt_u32_e32 vcc, s2, v62
	v_and_b32_e32 v4, 7, v62
	v_mad_u64_u32 v[2:3], s[2:3], v48, s90, v[2:3]
	v_cndmask_b32_e32 v5, v211, v252, vcc
	v_mad_i32_i24 v3, v49, s90, v3
	v_lshlrev_b32_e32 v110, 4, v4
	v_mov_b32_e32 v111, v0
	v_lshlrev_b32_e32 v56, 1, v5
	v_mov_b32_e32 v57, v0
	v_lshl_add_u64 v[42:43], v[2:3], 0, v[110:111]
	v_lshl_add_u64 v[2:3], s[68:69], 0, v[56:57]
	v_mov_b32_e32 v55, v0
	v_lshl_add_u64 v[2:3], v[54:55], 1, v[2:3]
	v_lshl_add_u64 v[2:3], v[2:3], 0, v[110:111]
	s_mov_b64 s[2:3], 0x9000000
	v_lshl_add_u64 v[44:45], v[2:3], 0, s[2:3]
	s_lshl_b32 s54, s5, 8
	v_lshl_add_u64 v[6:7], v[42:43], 0, s[54:55]
	v_lshl_add_u64 v[10:11], v[44:45], 0, s[54:55]
	global_load_dwordx4 v[30:33], v[6:7], off offset:768
	global_load_dwordx4 v[2:5], v[6:7], off offset:896
	global_load_dwordx4 v[38:41], v[6:7], off offset:1536
	s_nop 0
	global_load_dwordx4 v[6:9], v[6:7], off offset:1664
	s_nop 0
	global_load_dwordx4 v[34:37], v[10:11], off
	s_nop 0
	global_load_dwordx4 v[10:13], v[10:11], off offset:128
	v_sub_u32_e64 v47, s26, 3 clamp
	s_movk_i32 s2, 0x3c0
	v_readfirstlane_b32 s28, v47
	v_cmp_gt_i32_e64 s[38:39], s2, v62
	s_barrier
	s_mov_b64 s[2:3], exec
	v_and_b32_e32 v50, 31, v62
	v_cmp_ne_u32_e64 s[38:39], 31, v50
	v_lshl_add_u32 v47, v62, 2, s4
	v_mov_b32_e32 v57, 0
	v_mov_b32_e32 v65, 0
	s_movk_i32 s18, 0x1c0
	v_cmp_gt_u32_e64 s[20:21], s18, v62
	s_and_b64 s[16:17], s[20:21], s[38:39]
	v_add_u32_e32 v85, 0x200, v62
	s_mov_b32 s18, 0x88888889
	s_and_b64 exec, s[2:3], s[38:39]
	v_mul_hi_i32 v84, v62, s18
	v_add_u32_e32 v84, v84, v62
	v_lshrrev_b32_e32 v80, 31, v84
	v_ashrrev_i32_e32 v84, 8, v84
	v_add_u32_e32 v84, v84, v80
	v_mul_i32_i24_e32 v80, 0x1e0, v84
	v_sub_u32_e32 v80, v62, v80
	v_ashrrev_i32_e32 v80, 5, v80
	v_add_u32_e32 v84, s13, v84
	v_mad_u32_u24 v80, v84, 15, v80
	v_mad_u32_u24 v80, v80, 31, v50
	v_ashrrev_i32_e32 v81, 31, v80
	v_lshl_add_u64 v[80:81], v[80:81], 2, s[42:43]
	global_load_dword v57, v[80:81], off
	s_and_b64 exec, s[2:3], s[16:17]
	v_mul_hi_i32 v86, v85, s18
	v_add_u32_e32 v86, v86, v85
	v_lshrrev_b32_e32 v82, 31, v86
	v_ashrrev_i32_e32 v86, 8, v86
	v_add_u32_e32 v86, v86, v82
	v_mul_i32_i24_e32 v82, 0x1e0, v86
	v_sub_u32_e32 v82, v85, v82
	v_ashrrev_i32_e32 v82, 5, v82
	v_add_u32_e32 v86, s13, v86
	v_mad_u32_u24 v82, v86, 15, v82
	v_mad_u32_u24 v82, v82, 31, v50
	v_ashrrev_i32_e32 v83, 31, v82
	v_lshl_add_u64 v[82:83], v[82:83], 2, s[42:43]
	global_load_dword v65, v[82:83], off
	s_mov_b64 exec, s[2:3]
	s_waitcnt vmcnt(0)
	v_mul_f32_e32 v57, 0x3fb8aa3b, v57
	v_mul_f32_e32 v65, 0x3fb8aa3b, v65
	ds_write_b32 v47, v57
	s_and_b64 exec, s[2:3], s[20:21]
	ds_write_b32 v47, v65 offset:2048
	s_mov_b64 exec, s[2:3]
